# GLA pass 1 and 3 V-transpose staging loops unrolled with the four 16-byte loads issued first and counted waits; plus c10
# speedup vs baseline: 1.0162x; 1.0068x over previous
; __device__ __forceinline__ int tsw(int row) { return ((row >> 3) & 7) << 3; }
; __device__ __forceinline__ void gla_g1(const Args& a, unsigned char* lds, int tid, int lane, int wave) {
;     ...
;         for (int ch = tid; ch < 2048; ch += 512) { const int s = ch >> 5, d0 = (ch & 31) * 8; const u32x4 w = *(const u32x4*)(P + (size_t)(n * 64 + s) * NP + C_GV + h * 256 + d0);
;             VT[(d0 + 0) * 72 + (s ^ tsw(d0))] = (bf16_t)(w.x & 0xffff); VT[(d0 + 1) * 72 + (s ^ tsw(d0))] = (bf16_t)(w.x >> 16); VT[(d0 + 2) * 72 + (s ^ tsw(d0))] = (bf16_t)(w.y & 0xffff); VT[(d0 + 3) * 72 + (s ^ tsw(d0))] = (bf16_t)(w.y >> 16);
;             VT[(d0 + 4) * 72 + (s ^ tsw(d0))] = (bf16_t)(w.z & 0xffff); VT[(d0 + 5) * 72 + (s ^ tsw(d0))] = (bf16_t)(w.z >> 16); VT[(d0 + 6) * 72 + (s ^ tsw(d0))] = (bf16_t)(w.w & 0xffff); VT[(d0 + 7) * 72 + (s ^ tsw(d0))] = (bf16_t)(w.w >> 16); }
;         if (tid < 128) Dd[it * 128 + tid] = __expf(bc[63 * 128 + tid]);
.LBB0_334:
	v_add_u32_e32 v6, s31, v0
	v_mov_b64_e32 v[4:5], s[2:3]
	v_and_b32_e32 v3, 0xf8, v1
	v_mad_i64_i32 v[4:5], s[14:15], v6, s23, v[4:5]
	v_lshlrev_b32_e32 v8, 1, v3
	v_lshl_add_u64 v[4:5], v[4:5], 0, s[8:9]
	v_lshl_add_u64 v[4:5], v[4:5], 0, v[8:9]
	v_add_co_u32_e32 v4, vcc, s16, v4
	v_bitop3_b32 v8, v1, v0, 56 bitop3:0x6c
	s_nop 0
	v_addc_co_u32_e32 v5, vcc, 0, v5, vcc
	global_load_dwordx4 v[184:187], v[4:5], off offset:2048
	v_add_u32_e32 v2, 0x200, v2
	v_mul_u32_u24_e32 v3, 0x90, v3
	v_lshlrev_b32_e32 v8, 1, v8
	v_cmp_lt_u32_e32 vcc, s30, v2
	v_add_u32_e32 v1, 0x1000, v1
	v_add_u32_e32 v0, 16, v0
	v_add3_u32 v3, 0, v3, v8
	s_or_b64 s[12:13], vcc, s[12:13]
	v_mov_b32_e32 v200, v3
	v_add_u32_e32 v6, s31, v0
	v_mov_b64_e32 v[4:5], s[2:3]
	v_and_b32_e32 v3, 0xf8, v1
	v_mad_i64_i32 v[4:5], s[14:15], v6, s23, v[4:5]
	v_lshlrev_b32_e32 v8, 1, v3
	v_lshl_add_u64 v[4:5], v[4:5], 0, s[8:9]
	v_lshl_add_u64 v[4:5], v[4:5], 0, v[8:9]
	v_add_co_u32_e32 v4, vcc, s16, v4
	v_bitop3_b32 v8, v1, v0, 56 bitop3:0x6c
	s_nop 0
	v_addc_co_u32_e32 v5, vcc, 0, v5, vcc
	global_load_dwordx4 v[188:191], v[4:5], off offset:2048
	v_add_u32_e32 v2, 0x200, v2
	v_mul_u32_u24_e32 v3, 0x90, v3
	v_lshlrev_b32_e32 v8, 1, v8
	v_cmp_lt_u32_e32 vcc, s30, v2
	v_add_u32_e32 v1, 0x1000, v1
	v_add_u32_e32 v0, 16, v0
	v_add3_u32 v3, 0, v3, v8
	s_or_b64 s[12:13], vcc, s[12:13]
	v_mov_b32_e32 v201, v3
	v_add_u32_e32 v6, s31, v0
	v_mov_b64_e32 v[4:5], s[2:3]
	v_and_b32_e32 v3, 0xf8, v1
	v_mad_i64_i32 v[4:5], s[14:15], v6, s23, v[4:5]
	v_lshlrev_b32_e32 v8, 1, v3
	v_lshl_add_u64 v[4:5], v[4:5], 0, s[8:9]
	v_lshl_add_u64 v[4:5], v[4:5], 0, v[8:9]
	v_add_co_u32_e32 v4, vcc, s16, v4
	v_bitop3_b32 v8, v1, v0, 56 bitop3:0x6c
	s_nop 0
	v_addc_co_u32_e32 v5, vcc, 0, v5, vcc
	global_load_dwordx4 v[192:195], v[4:5], off offset:2048
	v_add_u32_e32 v2, 0x200, v2
	v_mul_u32_u24_e32 v3, 0x90, v3
	v_lshlrev_b32_e32 v8, 1, v8
	v_cmp_lt_u32_e32 vcc, s30, v2
	v_add_u32_e32 v1, 0x1000, v1
	v_add_u32_e32 v0, 16, v0
	v_add3_u32 v3, 0, v3, v8
	s_or_b64 s[12:13], vcc, s[12:13]
	v_mov_b32_e32 v202, v3
	v_add_u32_e32 v6, s31, v0
	v_mov_b64_e32 v[4:5], s[2:3]
	v_and_b32_e32 v3, 0xf8, v1
	v_mad_i64_i32 v[4:5], s[14:15], v6, s23, v[4:5]
	v_lshlrev_b32_e32 v8, 1, v3
	v_lshl_add_u64 v[4:5], v[4:5], 0, s[8:9]
	v_lshl_add_u64 v[4:5], v[4:5], 0, v[8:9]
	v_add_co_u32_e32 v4, vcc, s16, v4
	v_bitop3_b32 v8, v1, v0, 56 bitop3:0x6c
	s_nop 0
	v_addc_co_u32_e32 v5, vcc, 0, v5, vcc
	global_load_dwordx4 v[196:199], v[4:5], off offset:2048
	v_add_u32_e32 v2, 0x200, v2
	v_mul_u32_u24_e32 v3, 0x90, v3
	v_lshlrev_b32_e32 v8, 1, v8
	v_cmp_lt_u32_e32 vcc, s30, v2
	v_add_u32_e32 v1, 0x1000, v1
	v_add_u32_e32 v0, 16, v0
	v_add3_u32 v3, 0, v3, v8
	s_or_b64 s[12:13], vcc, s[12:13]
	v_mov_b32_e32 v203, v3
	s_waitcnt vmcnt(3)
	ds_write_b16 v200, v184 offset:57344
	ds_write_b16_d16_hi v200, v184 offset:57488
	ds_write_b16 v200, v185 offset:57632
	ds_write_b16_d16_hi v200, v185 offset:57776
	ds_write_b16 v200, v186 offset:57920
	ds_write_b16_d16_hi v200, v186 offset:58064
	ds_write_b16 v200, v187 offset:58208
	ds_write_b16_d16_hi v200, v187 offset:58352
	s_waitcnt vmcnt(2)
	ds_write_b16 v201, v188 offset:57344
	ds_write_b16_d16_hi v201, v188 offset:57488
	ds_write_b16 v201, v189 offset:57632
	ds_write_b16_d16_hi v201, v189 offset:57776
	ds_write_b16 v201, v190 offset:57920
	ds_write_b16_d16_hi v201, v190 offset:58064
	ds_write_b16 v201, v191 offset:58208
	ds_write_b16_d16_hi v201, v191 offset:58352
	s_waitcnt vmcnt(1)
	ds_write_b16 v202, v192 offset:57344
	ds_write_b16_d16_hi v202, v192 offset:57488
	ds_write_b16 v202, v193 offset:57632
	ds_write_b16_d16_hi v202, v193 offset:57776
	ds_write_b16 v202, v194 offset:57920
	ds_write_b16_d16_hi v202, v194 offset:58064
	ds_write_b16 v202, v195 offset:58208
	ds_write_b16_d16_hi v202, v195 offset:58352
	s_waitcnt vmcnt(0)
	ds_write_b16 v203, v196 offset:57344
	ds_write_b16_d16_hi v203, v196 offset:57488
	ds_write_b16 v203, v197 offset:57632
	ds_write_b16_d16_hi v203, v197 offset:57776
	ds_write_b16 v203, v198 offset:57920
	ds_write_b16_d16_hi v203, v198 offset:58064
	ds_write_b16 v203, v199 offset:58208
	ds_write_b16_d16_hi v203, v199 offset:58352
	s_or_b64 exec, exec, s[12:13]
	s_and_saveexec_b64 s[12:13], s[0:1]
	s_cbranch_execz .LBB0_322
	ds_read_b32 v0, v54 offset:36352
	s_waitcnt lgkmcnt(0)
	v_mul_f32_e32 v0, 0x3fb8aa3b, v0
	v_exp_f32_e32 v2, v0
	v_lshl_or_b32 v0, s10, 7, v128
	v_ashrrev_i32_e32 v1, 31, v0
	v_lshl_add_u64 v[0:1], v[0:1], 2, s[6:7]
	global_store_dword v[0:1], v2, off
	s_branch .LBB0_322

; __device__ __forceinline__ int tsw(int row) { return ((row >> 3) & 7) << 3; }
; __device__ __forceinline__ void gla_g1(const Args& a, unsigned char* lds, int tid, int lane, int wave) {
;     ...
;         for (int ch = tid; ch < 2048; ch += 512) { const int s = ch >> 5, d0 = (ch & 31) * 8; const u32x4 w = *(const u32x4*)(P + (size_t)(n * 64 + s) * NP + C_GV + h * 256 + d0);
;             VT[(d0 + 0) * 72 + (s ^ tsw(d0))] = (bf16_t)(w.x & 0xffff); VT[(d0 + 1) * 72 + (s ^ tsw(d0))] = (bf16_t)(w.x >> 16); VT[(d0 + 2) * 72 + (s ^ tsw(d0))] = (bf16_t)(w.y & 0xffff); VT[(d0 + 3) * 72 + (s ^ tsw(d0))] = (bf16_t)(w.y >> 16);
;             VT[(d0 + 4) * 72 + (s ^ tsw(d0))] = (bf16_t)(w.z & 0xffff); VT[(d0 + 5) * 72 + (s ^ tsw(d0))] = (bf16_t)(w.z >> 16); VT[(d0 + 6) * 72 + (s ^ tsw(d0))] = (bf16_t)(w.w & 0xffff); VT[(d0 + 7) * 72 + (s ^ tsw(d0))] = (bf16_t)(w.w >> 16); }
;         if (tid < 128) Dd[it * 128 + tid] = __expf(bc[63 * 128 + tid]);
.LBB0_771:
	v_add_u32_e32 v6, s31, v0
	v_mov_b64_e32 v[4:5], s[6:7]
	v_and_b32_e32 v3, 0xf8, v1
	v_mad_i64_i32 v[4:5], s[14:15], v6, s23, v[4:5]
	v_lshlrev_b32_e32 v8, 1, v3
	v_lshl_add_u64 v[4:5], v[4:5], 0, s[8:9]
	v_lshl_add_u64 v[4:5], v[4:5], 0, v[8:9]
	v_add_co_u32_e32 v4, vcc, s16, v4
	v_bitop3_b32 v8, v1, v0, 56 bitop3:0x6c
	s_nop 0
	v_addc_co_u32_e32 v5, vcc, 0, v5, vcc
	global_load_dwordx4 v[184:187], v[4:5], off offset:2048
	v_add_u32_e32 v2, 0x200, v2
	v_mul_u32_u24_e32 v3, 0x90, v3
	v_lshlrev_b32_e32 v8, 1, v8
	v_cmp_lt_u32_e32 vcc, s30, v2
	v_add_u32_e32 v1, 0x1000, v1
	v_add_u32_e32 v0, 16, v0
	v_add3_u32 v3, 0, v3, v8
	s_or_b64 s[12:13], vcc, s[12:13]
	v_mov_b32_e32 v200, v3
	v_add_u32_e32 v6, s31, v0
	v_mov_b64_e32 v[4:5], s[6:7]
	v_and_b32_e32 v3, 0xf8, v1
	v_mad_i64_i32 v[4:5], s[14:15], v6, s23, v[4:5]
	v_lshlrev_b32_e32 v8, 1, v3
	v_lshl_add_u64 v[4:5], v[4:5], 0, s[8:9]
	v_lshl_add_u64 v[4:5], v[4:5], 0, v[8:9]
	v_add_co_u32_e32 v4, vcc, s16, v4
	v_bitop3_b32 v8, v1, v0, 56 bitop3:0x6c
	s_nop 0
	v_addc_co_u32_e32 v5, vcc, 0, v5, vcc
	global_load_dwordx4 v[188:191], v[4:5], off offset:2048
	v_add_u32_e32 v2, 0x200, v2
	v_mul_u32_u24_e32 v3, 0x90, v3
	v_lshlrev_b32_e32 v8, 1, v8
	v_cmp_lt_u32_e32 vcc, s30, v2
	v_add_u32_e32 v1, 0x1000, v1
	v_add_u32_e32 v0, 16, v0
	v_add3_u32 v3, 0, v3, v8
	s_or_b64 s[12:13], vcc, s[12:13]
	v_mov_b32_e32 v201, v3
	v_add_u32_e32 v6, s31, v0
	v_mov_b64_e32 v[4:5], s[6:7]
	v_and_b32_e32 v3, 0xf8, v1
	v_mad_i64_i32 v[4:5], s[14:15], v6, s23, v[4:5]
	v_lshlrev_b32_e32 v8, 1, v3
	v_lshl_add_u64 v[4:5], v[4:5], 0, s[8:9]
	v_lshl_add_u64 v[4:5], v[4:5], 0, v[8:9]
	v_add_co_u32_e32 v4, vcc, s16, v4
	v_bitop3_b32 v8, v1, v0, 56 bitop3:0x6c
	s_nop 0
	v_addc_co_u32_e32 v5, vcc, 0, v5, vcc
	global_load_dwordx4 v[192:195], v[4:5], off offset:2048
	v_add_u32_e32 v2, 0x200, v2
	v_mul_u32_u24_e32 v3, 0x90, v3
	v_lshlrev_b32_e32 v8, 1, v8
	v_cmp_lt_u32_e32 vcc, s30, v2
	v_add_u32_e32 v1, 0x1000, v1
	v_add_u32_e32 v0, 16, v0
	v_add3_u32 v3, 0, v3, v8
	s_or_b64 s[12:13], vcc, s[12:13]
	v_mov_b32_e32 v202, v3
	v_add_u32_e32 v6, s31, v0
	v_mov_b64_e32 v[4:5], s[6:7]
	v_and_b32_e32 v3, 0xf8, v1
	v_mad_i64_i32 v[4:5], s[14:15], v6, s23, v[4:5]
	v_lshlrev_b32_e32 v8, 1, v3
	v_lshl_add_u64 v[4:5], v[4:5], 0, s[8:9]
	v_lshl_add_u64 v[4:5], v[4:5], 0, v[8:9]
	v_add_co_u32_e32 v4, vcc, s16, v4
	v_bitop3_b32 v8, v1, v0, 56 bitop3:0x6c
	s_nop 0
	v_addc_co_u32_e32 v5, vcc, 0, v5, vcc
	global_load_dwordx4 v[196:199], v[4:5], off offset:2048
	v_add_u32_e32 v2, 0x200, v2
	v_mul_u32_u24_e32 v3, 0x90, v3
	v_lshlrev_b32_e32 v8, 1, v8
	v_cmp_lt_u32_e32 vcc, s30, v2
	v_add_u32_e32 v1, 0x1000, v1
	v_add_u32_e32 v0, 16, v0
	v_add3_u32 v3, 0, v3, v8
	s_or_b64 s[12:13], vcc, s[12:13]
	v_mov_b32_e32 v203, v3
	s_waitcnt vmcnt(3)
	ds_write_b16 v200, v184 offset:57344
	ds_write_b16_d16_hi v200, v184 offset:57488
	ds_write_b16 v200, v185 offset:57632
	ds_write_b16_d16_hi v200, v185 offset:57776
	ds_write_b16 v200, v186 offset:57920
	ds_write_b16_d16_hi v200, v186 offset:58064
	ds_write_b16 v200, v187 offset:58208
	ds_write_b16_d16_hi v200, v187 offset:58352
	s_waitcnt vmcnt(2)
	ds_write_b16 v201, v188 offset:57344
	ds_write_b16_d16_hi v201, v188 offset:57488
	ds_write_b16 v201, v189 offset:57632
	ds_write_b16_d16_hi v201, v189 offset:57776
	ds_write_b16 v201, v190 offset:57920
	ds_write_b16_d16_hi v201, v190 offset:58064
	ds_write_b16 v201, v191 offset:58208
	ds_write_b16_d16_hi v201, v191 offset:58352
	s_waitcnt vmcnt(1)
	ds_write_b16 v202, v192 offset:57344
	ds_write_b16_d16_hi v202, v192 offset:57488
	ds_write_b16 v202, v193 offset:57632
	ds_write_b16_d16_hi v202, v193 offset:57776
	ds_write_b16 v202, v194 offset:57920
	ds_write_b16_d16_hi v202, v194 offset:58064
	ds_write_b16 v202, v195 offset:58208
	ds_write_b16_d16_hi v202, v195 offset:58352
	s_waitcnt vmcnt(0)
	ds_write_b16 v203, v196 offset:57344
	ds_write_b16_d16_hi v203, v196 offset:57488
	ds_write_b16 v203, v197 offset:57632
	ds_write_b16_d16_hi v203, v197 offset:57776
	ds_write_b16 v203, v198 offset:57920
	ds_write_b16_d16_hi v203, v198 offset:58064
	ds_write_b16 v203, v199 offset:58208
	ds_write_b16_d16_hi v203, v199 offset:58352
	s_or_b64 exec, exec, s[12:13]
	s_and_saveexec_b64 s[12:13], s[0:1]
	s_cbranch_execz .LBB0_759
	ds_read_b32 v0, v54 offset:36352
	s_waitcnt lgkmcnt(0)
	v_mul_f32_e32 v0, 0x3fb8aa3b, v0
	v_exp_f32_e32 v2, v0
	v_lshl_or_b32 v0, s10, 7, v128
	v_ashrrev_i32_e32 v1, 31, v0
	v_lshl_add_u64 v[0:1], v[0:1], 2, s[2:3]
	global_store_dword v[0:1], v2, off
	s_branch .LBB0_759

; __device__ __forceinline__ int tsw(int row) { return ((row >> 3) & 7) << 3; }
; __device__ __forceinline__ void gla_g3(const Args& a, unsigned char* lds, int tid, int lane, int wave) {
;     ...
;         for (int ch = tid; ch < 2048; ch += 512) { const int s = ch >> 5, d0 = (ch & 31) * 8; const u32x4 w = *(const u32x4*)(P + (size_t)(n * 64 + s) * NP + C_GV + h * 256 + d0);
;             VT[(d0 + 0) * 72 + (s ^ tsw(d0))] = (bf16_t)(w.x & 0xffff); VT[(d0 + 1) * 72 + (s ^ tsw(d0))] = (bf16_t)(w.x >> 16); VT[(d0 + 2) * 72 + (s ^ tsw(d0))] = (bf16_t)(w.y & 0xffff); VT[(d0 + 3) * 72 + (s ^ tsw(d0))] = (bf16_t)(w.y >> 16);
;             VT[(d0 + 4) * 72 + (s ^ tsw(d0))] = (bf16_t)(w.z & 0xffff); VT[(d0 + 5) * 72 + (s ^ tsw(d0))] = (bf16_t)(w.z >> 16); VT[(d0 + 6) * 72 + (s ^ tsw(d0))] = (bf16_t)(w.w & 0xffff); VT[(d0 + 7) * 72 + (s ^ tsw(d0))] = (bf16_t)(w.w >> 16); }
;         __syncthreads();
.LBB0_1931:
	v_add_u32_e32 v6, s27, v0
	v_mov_b64_e32 v[4:5], s[10:11]
	v_and_b32_e32 v3, 0xf8, v1
	s_lshl_b32 s22, s54, 1
	v_mad_i64_i32 v[4:5], s[56:57], v6, s50, v[4:5]
	v_lshlrev_b32_e32 v38, 1, v3
	v_lshl_add_u64 v[4:5], v[4:5], 0, s[22:23]
	v_lshl_add_u64 v[4:5], v[4:5], 0, v[38:39]
	v_add_co_u32_e32 v4, vcc, s33, v4
	v_bitop3_b32 v8, v1, v0, 56 bitop3:0x6c
	s_nop 0
	v_addc_co_u32_e32 v5, vcc, 0, v5, vcc
	global_load_dwordx4 v[184:187], v[4:5], off offset:2048
	v_add_u32_e32 v2, 0x200, v2
	v_mul_u32_u24_e32 v3, 0x90, v3
	v_lshlrev_b32_e32 v8, 1, v8
	v_cmp_lt_u32_e32 vcc, s51, v2
	v_add_u32_e32 v1, 0x1000, v1
	v_add_u32_e32 v0, 16, v0
	v_add3_u32 v3, s39, v3, v8
	s_or_b64 s[40:41], vcc, s[40:41]
	v_mov_b32_e32 v200, v3
	v_add_u32_e32 v6, s27, v0
	v_mov_b64_e32 v[4:5], s[10:11]
	v_and_b32_e32 v3, 0xf8, v1
	s_lshl_b32 s22, s54, 1
	v_mad_i64_i32 v[4:5], s[56:57], v6, s50, v[4:5]
	v_lshlrev_b32_e32 v38, 1, v3
	v_lshl_add_u64 v[4:5], v[4:5], 0, s[22:23]
	v_lshl_add_u64 v[4:5], v[4:5], 0, v[38:39]
	v_add_co_u32_e32 v4, vcc, s33, v4
	v_bitop3_b32 v8, v1, v0, 56 bitop3:0x6c
	s_nop 0
	v_addc_co_u32_e32 v5, vcc, 0, v5, vcc
	global_load_dwordx4 v[188:191], v[4:5], off offset:2048
	v_add_u32_e32 v2, 0x200, v2
	v_mul_u32_u24_e32 v3, 0x90, v3
	v_lshlrev_b32_e32 v8, 1, v8
	v_cmp_lt_u32_e32 vcc, s51, v2
	v_add_u32_e32 v1, 0x1000, v1
	v_add_u32_e32 v0, 16, v0
	v_add3_u32 v3, s39, v3, v8
	s_or_b64 s[40:41], vcc, s[40:41]
	v_mov_b32_e32 v201, v3
	v_add_u32_e32 v6, s27, v0
	v_mov_b64_e32 v[4:5], s[10:11]
	v_and_b32_e32 v3, 0xf8, v1
	s_lshl_b32 s22, s54, 1
	v_mad_i64_i32 v[4:5], s[56:57], v6, s50, v[4:5]
	v_lshlrev_b32_e32 v38, 1, v3
	v_lshl_add_u64 v[4:5], v[4:5], 0, s[22:23]
	v_lshl_add_u64 v[4:5], v[4:5], 0, v[38:39]
	v_add_co_u32_e32 v4, vcc, s33, v4
	v_bitop3_b32 v8, v1, v0, 56 bitop3:0x6c
	s_nop 0
	v_addc_co_u32_e32 v5, vcc, 0, v5, vcc
	global_load_dwordx4 v[192:195], v[4:5], off offset:2048
	v_add_u32_e32 v2, 0x200, v2
	v_mul_u32_u24_e32 v3, 0x90, v3
	v_lshlrev_b32_e32 v8, 1, v8
	v_cmp_lt_u32_e32 vcc, s51, v2
	v_add_u32_e32 v1, 0x1000, v1
	v_add_u32_e32 v0, 16, v0
	v_add3_u32 v3, s39, v3, v8
	s_or_b64 s[40:41], vcc, s[40:41]
	v_mov_b32_e32 v202, v3
	v_add_u32_e32 v6, s27, v0
	v_mov_b64_e32 v[4:5], s[10:11]
	v_and_b32_e32 v3, 0xf8, v1
	s_lshl_b32 s22, s54, 1
	v_mad_i64_i32 v[4:5], s[56:57], v6, s50, v[4:5]
	v_lshlrev_b32_e32 v38, 1, v3
	v_lshl_add_u64 v[4:5], v[4:5], 0, s[22:23]
	v_lshl_add_u64 v[4:5], v[4:5], 0, v[38:39]
	v_add_co_u32_e32 v4, vcc, s33, v4
	v_bitop3_b32 v8, v1, v0, 56 bitop3:0x6c
	s_nop 0
	v_addc_co_u32_e32 v5, vcc, 0, v5, vcc
	global_load_dwordx4 v[196:199], v[4:5], off offset:2048
	v_add_u32_e32 v2, 0x200, v2
	v_mul_u32_u24_e32 v3, 0x90, v3
	v_lshlrev_b32_e32 v8, 1, v8
	v_cmp_lt_u32_e32 vcc, s51, v2
	v_add_u32_e32 v1, 0x1000, v1
	v_add_u32_e32 v0, 16, v0
	v_add3_u32 v3, s39, v3, v8
	s_or_b64 s[40:41], vcc, s[40:41]
	v_mov_b32_e32 v203, v3
	s_waitcnt vmcnt(3)
	ds_write_b16 v200, v184
	ds_write_b16_d16_hi v200, v184 offset:144
	ds_write_b16 v200, v185 offset:288
	ds_write_b16_d16_hi v200, v185 offset:432
	ds_write_b16 v200, v186 offset:576
	ds_write_b16_d16_hi v200, v186 offset:720
	ds_write_b16 v200, v187 offset:864
	ds_write_b16_d16_hi v200, v187 offset:1008
	s_waitcnt vmcnt(2)
	ds_write_b16 v201, v188
	ds_write_b16_d16_hi v201, v188 offset:144
	ds_write_b16 v201, v189 offset:288
	ds_write_b16_d16_hi v201, v189 offset:432
	ds_write_b16 v201, v190 offset:576
	ds_write_b16_d16_hi v201, v190 offset:720
	ds_write_b16 v201, v191 offset:864
	ds_write_b16_d16_hi v201, v191 offset:1008
	s_waitcnt vmcnt(1)
	ds_write_b16 v202, v192
	ds_write_b16_d16_hi v202, v192 offset:144
	ds_write_b16 v202, v193 offset:288
	ds_write_b16_d16_hi v202, v193 offset:432
	ds_write_b16 v202, v194 offset:576
	ds_write_b16_d16_hi v202, v194 offset:720
	ds_write_b16 v202, v195 offset:864
	ds_write_b16_d16_hi v202, v195 offset:1008
	s_waitcnt vmcnt(0)
	ds_write_b16 v203, v196
	ds_write_b16_d16_hi v203, v196 offset:144
	ds_write_b16 v203, v197 offset:288
	ds_write_b16_d16_hi v203, v197 offset:432
	ds_write_b16 v203, v198 offset:576
	ds_write_b16_d16_hi v203, v198 offset:720
	ds_write_b16 v203, v199 offset:864
	ds_write_b16_d16_hi v203, v199 offset:1008
	s_or_b64 exec, exec, s[40:41]
	s_waitcnt lgkmcnt(0)
	s_barrier
; __device__ __forceinline__ unsigned f2bf(float f) { unsigned u = __builtin_bit_cast(unsigned, f); return (u + 0x7fffu + ((u >> 16) & 1u)) >> 16; }
; __device__ __forceinline__ f32x4 mfma16(bf16x8 a, bf16x8 b, f32x4 c) { return __builtin_amdgcn_mfma_f32_16x16x32_bf16(a, b, c, 0, 0, 0); }
; __device__ __forceinline__ void gla_g3(const Args& a, unsigned char* lds, int tid, int lane, int wave) {
;     ...
;         for (int ti = 0; ti < 2; ++ti) { const int id = wave * 2 + ti, mt = id >> 2, nt = id & 3;
;             f32x4 c = {0.f, 0.f, 0.f, 0.f};
; #pragma unroll
;             for (int ks = 0; ks < 4; ++ks) c = mfma16(*(const bf16x8*)(Q + (mt * 16 + l15) * 136 + ks * 32 + q * 8), *(const bf16x8*)(Kk + (nt * 16 + l15) * 136 + ks * 32 + q * 8), c);
; #pragma unroll
;             for (int j = 0; j < 4; ++j) { const int t = mt * 16 + q * 4 + j, s = nt * 16 + l15; ATS[t * 72 + s] = (bf16_t)f2bf(s <= t ? c[j] : 0.f); } }
;         __syncthreads();
;         const int mt = wave & 3, half = wave >> 2;
;         bf16_t grv[4][8];
; #pragma unroll
;         for (int j = 0; j < 4; ++j)
; #pragma unroll
;             for (int i = 0; i < 8; ++i) grv[j][i] = P[(size_t)(n * 64 + mt * 16 + q * 4 + j) * NP + C_GR + h * 256 + (half * 8 + i) * 16 + l15];
;         f32x4 acc[8];
; #pragma unroll
;         for (int i = 0; i < 8; ++i) acc[i] = (f32x4){0.f, 0.f, 0.f, 0.f};
;         const bf16_t* Sg = (const bf16_t*)a.out + (size_t)it * 32768;
; #pragma unroll
;         for (int ks = 0; ks < 4; ++ks) { const bf16x8 aq = *(const bf16x8*)(Q + (mt * 16 + l15) * 136 + ks * 32 + q * 8);
; #pragma unroll
;             for (int i = 0; i < 8; ++i) acc[i] = mfma16(aq, *(const bf16x8*)(Sg + ((half * 8 + i) * 16 + l15) * 128 + ks * 32 + q * 8), acc[i]); }
	ds_read_b128 v[0:3], v36 offset:38912
	ds_read_b128 v[4:7], v36 offset:38976
	ds_read_b128 v[8:11], v112 offset:56320
	ds_read_b128 v[12:15], v112 offset:56384
	s_waitcnt lgkmcnt(1)
	v_mfma_f32_16x16x32_bf16 v[0:3], v[0:3], v[8:11], 0
	ds_read_b128 v[8:11], v36 offset:39040
	ds_read_b128 v[16:19], v36 offset:39104
	s_lshl_b64 s[40:41], s[2:3], 16
	v_lshl_add_u64 v[66:67], v[42:43], 0, s[40:41]
	s_waitcnt lgkmcnt(2)
	v_mfma_f32_16x16x32_bf16 v[0:3], v[4:7], v[12:15], v[0:3]
	ds_read_b128 v[4:7], v112 offset:56448
	ds_read_b128 v[12:15], v112 offset:56512
	v_lshl_add_u64 v[140:141], v[40:41], 1, v[66:67]
	v_lshl_add_u64 v[24:25], v[66:67], 0, v[54:55]
	s_waitcnt lgkmcnt(1)
	v_mfma_f32_16x16x32_bf16 v[0:3], v[8:11], v[4:7], v[0:3]
	v_lshl_add_u64 v[28:29], v[66:67], 0, v[56:57]
	v_lshl_add_u64 v[32:33], v[66:67], 0, v[58:59]
	v_lshl_add_u64 v[120:121], v[66:67], 0, v[60:61]
	s_waitcnt lgkmcnt(0)
	v_mfma_f32_16x16x32_bf16 v[0:3], v[16:19], v[12:15], v[0:3]
	v_lshl_add_u64 v[124:125], v[66:67], 0, v[62:63]
	v_lshl_add_u64 v[142:143], v[66:67], 0, 64
	v_lshl_add_u64 v[132:133], v[142:143], 0, v[50:51]
	v_lshl_add_u64 v[136:137], v[142:143], 0, v[52:53]
	v_lshl_add_u64 v[144:145], v[142:143], 0, v[54:55]
	s_nop 2
	v_cndmask_b32_e64 v0, v0, 0, s[4:5]
	v_cndmask_b32_e64 v1, v1, 0, s[6:7]
	v_cndmask_b32_e64 v2, v2, 0, s[8:9]
	v_cndmask_b32_e64 v3, v3, 0, s[12:13]
	v_bfe_u32 v4, v0, 16, 1
	v_bfe_u32 v5, v1, 16, 1
	v_bfe_u32 v6, v2, 16, 1
	v_bfe_u32 v7, v3, 16, 1
	v_add3_u32 v0, v0, v4, s52
	v_add3_u32 v1, v1, v5, s52
	v_add3_u32 v2, v2, v6, s52
	ds_write_b16_d16_hi v113, v0
	ds_write_b16_d16_hi v113, v1 offset:144
	ds_write_b16_d16_hi v113, v2 offset:288
	v_add3_u32 v0, v3, v7, s52
	ds_write_b16_d16_hi v113, v0 offset:432
	ds_read_b128 v[0:3], v36 offset:38912
	ds_read_b128 v[4:7], v36 offset:38976
	ds_read_b128 v[8:11], v112 offset:60672
	ds_read_b128 v[12:15], v112 offset:60736
	s_waitcnt lgkmcnt(1)
	v_mfma_f32_16x16x32_bf16 v[0:3], v[0:3], v[8:11], 0
	ds_read_b128 v[8:11], v36 offset:39040
	ds_read_b128 v[16:19], v36 offset:39104
	s_lshl_b32 s3, s2, 4
	s_andn2_b32 s3, s3, 63
	s_waitcnt lgkmcnt(2)
	v_mfma_f32_16x16x32_bf16 v[0:3], v[4:7], v[12:15], v[0:3]
	ds_read_b128 v[4:7], v112 offset:60800
	ds_read_b128 v[12:15], v112 offset:60864
	v_or_b32_e32 v38, s3, v37
	v_mov_b32_e32 v49, v39
	s_waitcnt lgkmcnt(1)
	v_mfma_f32_16x16x32_bf16 v[0:3], v[8:11], v[4:7], v[0:3]
	v_lshl_add_u64 v[8:9], v[66:67], 0, v[52:53]
	s_mov_b32 s27, s23
	v_or_b32_e32 v47, 1, v38
	s_waitcnt lgkmcnt(0)
	v_mfma_f32_16x16x32_bf16 v[0:3], v[16:19], v[12:15], v[0:3]
	s_nop 7
	v_cndmask_b32_e64 v0, v0, 0, s[14:15]
	v_cndmask_b32_e64 v1, v1, 0, s[16:17]
	v_cndmask_b32_e64 v2, v2, 0, s[18:19]
	v_cndmask_b32_e64 v3, v3, 0, s[20:21]
	v_bfe_u32 v4, v0, 16, 1
	v_bfe_u32 v5, v1, 16, 1
	v_bfe_u32 v6, v2, 16, 1
	v_bfe_u32 v7, v3, 16, 1
	v_add3_u32 v0, v0, v4, s52
	v_add3_u32 v1, v1, v5, s52
	v_add3_u32 v2, v2, v6, s52
	v_add3_u32 v3, v3, v7, s52
	ds_write_b16_d16_hi v77, v0
	ds_write_b16_d16_hi v78, v1
	ds_write_b16_d16_hi v79, v2
	ds_write_b16_d16_hi v80, v3
	s_waitcnt lgkmcnt(0)
	s_barrier
	global_load_dwordx4 v[0:3], v[140:141], off
	v_lshl_add_u64 v[4:5], v[66:67], 0, v[50:51]
	global_load_dwordx4 v[4:7], v[4:5], off
	ds_read_b128 v[12:15], v68 offset:38912
	global_load_dwordx4 v[8:11], v[8:9], off
	ds_read_b128 v[16:19], v68 offset:38976
	global_load_dwordx4 v[24:27], v[24:25], off
	ds_read_b128 v[150:153], v69
	global_load_dwordx4 v[28:31], v[28:29], off
	s_waitcnt vmcnt(4) lgkmcnt(2)
	v_mfma_f32_16x16x32_bf16 v[0:3], v[12:15], v[0:3], 0
	global_load_dwordx4 v[32:35], v[32:33], off
	s_nop 0
	global_load_dwordx4 v[120:123], v[120:121], off
	s_waitcnt vmcnt(5)
	v_mfma_f32_16x16x32_bf16 v[4:7], v[12:15], v[4:7], 0
	global_load_dwordx4 v[124:127], v[124:125], off
	s_nop 0
	global_load_dwordx4 v[20:23], v[140:141], off offset:64
	s_waitcnt vmcnt(6)
	v_mfma_f32_16x16x32_bf16 v[8:11], v[12:15], v[8:11], 0
	global_load_dwordx4 v[132:135], v[132:133], off
	s_nop 0
	global_load_dwordx4 v[136:139], v[136:137], off
	s_waitcnt vmcnt(7)
	v_mfma_f32_16x16x32_bf16 v[24:27], v[12:15], v[24:27], 0
	s_waitcnt vmcnt(6)
	v_mfma_f32_16x16x32_bf16 v[28:31], v[12:15], v[28:31], 0
	s_waitcnt vmcnt(5)
	v_mfma_f32_16x16x32_bf16 v[32:35], v[12:15], v[32:35], 0
	s_waitcnt vmcnt(4)
	v_mfma_f32_16x16x32_bf16 v[120:123], v[12:15], v[120:123], 0
	s_waitcnt vmcnt(3)
	v_mfma_f32_16x16x32_bf16 v[12:15], v[12:15], v[124:127], 0
	global_load_dwordx4 v[124:127], v[144:145], off
	v_lshl_add_u64 v[144:145], v[142:143], 0, v[56:57]
	s_waitcnt vmcnt(3) lgkmcnt(1)
	v_mfma_f32_16x16x32_bf16 v[0:3], v[16:19], v[20:23], v[0:3]
	global_load_dwordx4 v[20:23], v[144:145], off
	v_lshl_add_u64 v[144:145], v[142:143], 0, v[58:59]
	s_waitcnt vmcnt(3)
	v_mfma_f32_16x16x32_bf16 v[4:7], v[16:19], v[132:135], v[4:7]
	global_load_dwordx4 v[132:135], v[144:145], off
	v_lshl_add_u64 v[144:145], v[142:143], 0, v[60:61]
	v_lshl_add_u64 v[142:143], v[142:143], 0, v[62:63]
	s_waitcnt vmcnt(3)
	v_mfma_f32_16x16x32_bf16 v[8:11], v[16:19], v[136:139], v[8:11]
	global_load_dwordx4 v[136:139], v[144:145], off
	v_lshl_add_u64 v[144:145], v[66:67], 0, s[30:31]
	v_lshl_add_u64 v[146:147], v[144:145], 0, v[54:55]
	s_waitcnt vmcnt(3)
	v_mfma_f32_16x16x32_bf16 v[24:27], v[16:19], v[124:127], v[24:27]
	global_load_dwordx4 v[124:127], v[142:143], off
	v_lshl_add_u64 v[142:143], v[144:145], 0, v[50:51]
	v_lshl_add_u64 v[66:67], v[66:67], 0, s[34:35]
	s_waitcnt vmcnt(3)
	v_mfma_f32_16x16x32_bf16 v[20:23], v[16:19], v[20:23], v[28:31]
	s_nop 2
	global_load_dwordx4 v[28:31], v[140:141], off offset:128
	s_waitcnt vmcnt(3)
; __device__ __forceinline__ f32x4 mfma16(bf16x8 a, bf16x8 b, f32x4 c) { return __builtin_amdgcn_mfma_f32_16x16x32_bf16(a, b, c, 0, 0, 0); }
; __device__ __forceinline__ int tsw(int row) { return ((row >> 3) & 7) << 3; }
; __device__ __forceinline__ void gla_g3(const Args& a, unsigned char* lds, int tid, int lane, int wave) {
;     ...
;             for (int i = 0; i < 8; ++i) grv[j][i] = P[(size_t)(n * 64 + mt * 16 + q * 4 + j) * NP + C_GR + h * 256 + (half * 8 + i) * 16 + l15];
;         f32x4 acc[8];
; #pragma unroll
;         for (int i = 0; i < 8; ++i) acc[i] = (f32x4){0.f, 0.f, 0.f, 0.f};
;         const bf16_t* Sg = (const bf16_t*)a.out + (size_t)it * 32768;
; #pragma unroll
;         for (int ks = 0; ks < 4; ++ks) { const bf16x8 aq = *(const bf16x8*)(Q + (mt * 16 + l15) * 136 + ks * 32 + q * 8);
; #pragma unroll
;             for (int i = 0; i < 8; ++i) acc[i] = mfma16(aq, *(const bf16x8*)(Sg + ((half * 8 + i) * 16 + l15) * 128 + ks * 32 + q * 8), acc[i]); }
; #pragma unroll
;         for (int ks = 0; ks < 2; ++ks) { const bf16x8 at = *(const bf16x8*)(ATS + (mt * 16 + l15) * 72 + ks * 32 + q * 8);
; #pragma unroll
;             for (int i = 0; i < 8; ++i) { const int vr = (half * 8 + i) * 16 + l15; acc[i] = mfma16(at, *(const bf16x8*)(VT + vr * 72 + ((ks * 32 + q * 8) ^ tsw(vr))), acc[i]); } }
	v_mfma_f32_16x16x32_bf16 v[32:35], v[16:19], v[132:135], v[32:35]
	global_load_dwordx4 v[132:135], v[142:143], off
	v_lshl_add_u64 v[142:143], v[144:145], 0, v[52:53]
	s_waitcnt vmcnt(3)
	v_mfma_f32_16x16x32_bf16 v[120:123], v[16:19], v[136:139], v[120:123]
	ds_read_b128 v[136:139], v68 offset:39040
	s_waitcnt vmcnt(2)
	v_mfma_f32_16x16x32_bf16 v[12:15], v[16:19], v[124:127], v[12:15]
	global_load_dwordx4 v[16:19], v[142:143], off
	ds_read_b128 v[124:127], v68 offset:39104
	global_load_dwordx4 v[140:143], v[140:141], off offset:192
	s_waitcnt vmcnt(3) lgkmcnt(1)
	v_mfma_f32_16x16x32_bf16 v[0:3], v[136:139], v[28:31], v[0:3]
	global_load_dwordx4 v[28:31], v[146:147], off
	v_lshl_add_u64 v[146:147], v[144:145], 0, v[56:57]
	s_waitcnt vmcnt(3)
	v_mfma_f32_16x16x32_bf16 v[4:7], v[136:139], v[132:135], v[4:7]
	global_load_dwordx4 v[132:135], v[146:147], off
	v_lshl_add_u64 v[146:147], v[144:145], 0, v[58:59]
	s_waitcnt vmcnt(3)
	v_mfma_f32_16x16x32_bf16 v[8:11], v[136:139], v[16:19], v[8:11]
	global_load_dwordx4 v[16:19], v[146:147], off
	v_lshl_add_u64 v[146:147], v[144:145], 0, v[60:61]
	v_lshl_add_u64 v[144:145], v[144:145], 0, v[62:63]
	s_waitcnt vmcnt(2)
	v_mfma_f32_16x16x32_bf16 v[24:27], v[136:139], v[28:31], v[24:27]
	global_load_dwordx4 v[28:31], v[146:147], off
	s_waitcnt vmcnt(2)
	v_mfma_f32_16x16x32_bf16 v[20:23], v[136:139], v[132:135], v[20:23]
	global_load_dwordx4 v[132:135], v[144:145], off
	s_waitcnt vmcnt(2)
	v_mfma_f32_16x16x32_bf16 v[16:19], v[136:139], v[16:19], v[32:35]
	s_nop 2
	v_lshl_add_u64 v[32:33], v[66:67], 0, v[50:51]
	global_load_dwordx4 v[32:35], v[32:33], off
	s_waitcnt vmcnt(2)
	v_mfma_f32_16x16x32_bf16 v[28:31], v[136:139], v[28:31], v[120:123]
	s_nop 2
	v_lshl_add_u64 v[120:121], v[66:67], 0, v[52:53]
	global_load_dwordx4 v[120:123], v[120:121], off
	s_waitcnt vmcnt(2)
	v_mfma_f32_16x16x32_bf16 v[12:15], v[136:139], v[132:135], v[12:15]
	v_lshl_add_u64 v[132:133], v[66:67], 0, v[54:55]
	global_load_dwordx4 v[132:135], v[132:133], off
	v_lshl_add_u64 v[136:137], v[66:67], 0, v[56:57]
	s_waitcnt vmcnt(2) lgkmcnt(0)
	v_mfma_f32_16x16x32_bf16 v[4:7], v[124:127], v[32:35], v[4:7]
	v_lshl_add_u64 v[32:33], v[66:67], 0, v[58:59]
	global_load_dwordx4 v[32:35], v[32:33], off
	s_waitcnt vmcnt(2)
	v_mfma_f32_16x16x32_bf16 v[8:11], v[124:127], v[120:123], v[8:11]
	v_lshl_add_u64 v[120:121], v[66:67], 0, v[60:61]
	global_load_dwordx4 v[120:123], v[120:121], off
	v_lshl_add_u64 v[66:67], v[66:67], 0, v[62:63]
	s_waitcnt vmcnt(2)
	v_mfma_f32_16x16x32_bf16 v[24:27], v[124:127], v[132:135], v[24:27]
	global_load_dwordx4 v[132:135], v[66:67], off
	s_nop 0
	global_load_dwordx4 v[136:139], v[136:137], off
	v_mfma_f32_16x16x32_bf16 v[0:3], v[124:127], v[140:143], v[0:3]
	v_mov_b64_e32 v[142:143], s[10:11]
	s_waitcnt vmcnt(3)
	v_mfma_f32_16x16x32_bf16 v[16:19], v[124:127], v[32:35], v[16:19]
	v_mad_i64_i32 v[32:33], s[40:41], v38, s50, v[142:143]
	v_lshl_add_u64 v[66:67], v[32:33], 0, s[22:23]
	ds_read_b128 v[32:35], v81
	s_waitcnt vmcnt(2)
	v_mfma_f32_16x16x32_bf16 v[28:31], v[124:127], v[120:123], v[28:31]
	ds_read_b128 v[120:123], v82
	ds_read_b128 v[154:157], v69 offset:64
	v_lshl_add_u64 v[66:67], v[66:67], 0, v[48:49]
	v_lshl_add_u64 v[66:67], v[66:67], 0, s[26:27]
	s_waitcnt lgkmcnt(2)
	v_mfma_f32_16x16x32_bf16 v[0:3], v[150:153], v[32:35], v[0:3]
	ds_read_b128 v[32:35], v83
	s_waitcnt lgkmcnt(2)
	v_mfma_f32_16x16x32_bf16 v[4:7], v[150:153], v[120:123], v[4:7]
	ds_read_b128 v[120:123], v84
	s_waitcnt vmcnt(1)
	v_mfma_f32_16x16x32_bf16 v[12:15], v[124:127], v[132:135], v[12:15]
	v_lshl_add_u64 v[132:133], v[66:67], 0, s[28:29]
	v_add_co_u32_e32 v66, vcc, s37, v66
	s_waitcnt vmcnt(0)
	v_mfma_f32_16x16x32_bf16 v[20:23], v[124:127], v[136:139], v[20:23]
	v_addc_co_u32_e32 v67, vcc, 0, v67, vcc
	s_waitcnt lgkmcnt(1)
	v_mfma_f32_16x16x32_bf16 v[8:11], v[150:153], v[32:35], v[8:11]
	global_load_ushort v124, v[66:67], off
	global_load_ushort v127, v[132:133], off offset:32
	s_nop 0
	global_load_ushort v67, v[132:133], off offset:64
	global_load_ushort v66, v[132:133], off offset:96
	global_load_ushort v35, v[132:133], off offset:128
	global_load_ushort v34, v[132:133], off offset:160
	global_load_ushort v33, v[132:133], off offset:192
	global_load_ushort v32, v[132:133], off offset:224
	v_mad_i64_i32 v[132:133], s[40:41], v47, s50, v[142:143]
	s_waitcnt lgkmcnt(0)
	v_mfma_f32_16x16x32_bf16 v[120:123], v[150:153], v[120:123], v[24:27]
	v_lshl_add_u64 v[136:137], v[132:133], 0, s[22:23]
	ds_read_b128 v[132:135], v86
	s_nop 0
	ds_read_b128 v[24:27], v85
	s_waitcnt lgkmcnt(0)
	v_mfma_f32_16x16x32_bf16 v[158:161], v[150:153], v[24:27], v[20:23]
	s_nop 2
	v_lshl_add_u64 v[20:21], v[136:137], 0, v[48:49]
	v_lshl_add_u64 v[20:21], v[20:21], 0, s[26:27]
	v_add_co_u32_e32 v26, vcc, s37, v20
	v_lshl_add_u64 v[24:25], v[20:21], 0, s[28:29]
	v_mfma_f32_16x16x32_bf16 v[162:165], v[150:153], v[132:135], v[16:19]
	v_addc_co_u32_e32 v27, vcc, 0, v21, vcc
	ds_read_b128 v[20:23], v88
	s_nop 0
	ds_read_b128 v[16:19], v87
	s_waitcnt lgkmcnt(0)
; __device__ __forceinline__ f32x4 mfma16(bf16x8 a, bf16x8 b, f32x4 c) { return __builtin_amdgcn_mfma_f32_16x16x32_bf16(a, b, c, 0, 0, 0); }
; __device__ __forceinline__ int tsw(int row) { return ((row >> 3) & 7) << 3; }
; __device__ __forceinline__ void gla_g3(const Args& a, unsigned char* lds, int tid, int lane, int wave) {
;     ...
;             for (int i = 0; i < 8; ++i) grv[j][i] = P[(size_t)(n * 64 + mt * 16 + q * 4 + j) * NP + C_GR + h * 256 + (half * 8 + i) * 16 + l15];
;         f32x4 acc[8];
; #pragma unroll
;         for (int i = 0; i < 8; ++i) acc[i] = (f32x4){0.f, 0.f, 0.f, 0.f};
;         const bf16_t* Sg = (const bf16_t*)a.out + (size_t)it * 32768;
; #pragma unroll
;         for (int ks = 0; ks < 4; ++ks) { const bf16x8 aq = *(const bf16x8*)(Q + (mt * 16 + l15) * 136 + ks * 32 + q * 8);
; #pragma unroll
;             for (int i = 0; i < 8; ++i) acc[i] = mfma16(aq, *(const bf16x8*)(Sg + ((half * 8 + i) * 16 + l15) * 128 + ks * 32 + q * 8), acc[i]); }
; #pragma unroll
;         for (int ks = 0; ks < 2; ++ks) { const bf16x8 at = *(const bf16x8*)(ATS + (mt * 16 + l15) * 72 + ks * 32 + q * 8);
; #pragma unroll
;             for (int i = 0; i < 8; ++i) { const int vr = (half * 8 + i) * 16 + l15; acc[i] = mfma16(at, *(const bf16x8*)(VT + vr * 72 + ((ks * 32 + q * 8) ^ tsw(vr))), acc[i]); } }
;         float ssq[4];
; #pragma unroll
;         for (int j = 0; j < 4; ++j) { float s = 0.f;
; #pragma unroll
;             for (int i = 0; i < 8; ++i) s += acc[i][j] * acc[i][j];
;             s += __shfl_xor(s, 1); s += __shfl_xor(s, 2); s += __shfl_xor(s, 4); s += __shfl_xor(s, 8); ssq[j] = s; }
;         if (l15 == 0) {
; #pragma unroll
;             for (int j = 0; j < 4; ++j) RS[(mt * 16 + q * 4 + j) * 2 + half] = ssq[j]; }
	v_mfma_f32_16x16x32_bf16 v[166:169], v[150:153], v[16:19], v[28:31]
	global_load_ushort v149, v[26:27], off
	global_load_ushort v148, v[24:25], off offset:32
	global_load_ushort v147, v[24:25], off offset:64
	global_load_ushort v146, v[24:25], off offset:96
	global_load_ushort v145, v[24:25], off offset:128
	global_load_ushort v144, v[24:25], off offset:160
	global_load_ushort v141, v[24:25], off offset:192
	global_load_ushort v137, v[24:25], off offset:224
	v_or_b32_e32 v16, 2, v38
	v_mad_i64_i32 v[16:17], s[40:41], v16, s50, v[142:143]
	v_mfma_f32_16x16x32_bf16 v[150:153], v[150:153], v[20:23], v[12:15]
	v_lshl_add_u64 v[20:21], v[16:17], 0, s[22:23]
	ds_read_b128 v[16:19], v90
	s_nop 0
	ds_read_b128 v[12:15], v89
	s_waitcnt lgkmcnt(0)
	v_mfma_f32_16x16x32_bf16 v[28:31], v[154:157], v[12:15], v[0:3]
	s_nop 2
	v_lshl_add_u64 v[0:1], v[20:21], 0, v[48:49]
	v_lshl_add_u64 v[12:13], v[0:1], 0, s[26:27]
	ds_read_b128 v[0:3], v91
	v_lshl_add_u64 v[14:15], v[12:13], 0, s[28:29]
	v_mfma_f32_16x16x32_bf16 v[24:27], v[154:157], v[16:19], v[4:7]
	v_add_co_u32_e32 v12, vcc, s37, v12
	s_nop 1
	ds_read_b128 v[4:7], v92
	v_addc_co_u32_e32 v13, vcc, 0, v13, vcc
	s_waitcnt lgkmcnt(1)
	v_mfma_f32_16x16x32_bf16 v[20:23], v[154:157], v[0:3], v[8:11]
	global_load_ushort v139, v[12:13], off
	global_load_ushort v138, v[14:15], off offset:32
	global_load_ushort v134, v[14:15], off offset:64
	global_load_ushort v133, v[14:15], off offset:96
	global_load_ushort v131, v[14:15], off offset:128
	global_load_ushort v129, v[14:15], off offset:160
	global_load_ushort v126, v[14:15], off offset:192
	global_load_ushort v125, v[14:15], off offset:224
	ds_read_b128 v[0:3], v93
	v_or_b32_e32 v8, 3, v38
	s_waitcnt lgkmcnt(1)
	v_mfma_f32_16x16x32_bf16 v[16:19], v[154:157], v[4:7], v[120:123]
	v_mad_i64_i32 v[4:5], s[40:41], v8, s50, v[142:143]
	v_lshl_add_u64 v[8:9], v[4:5], 0, s[22:23]
	s_waitcnt lgkmcnt(0)
	v_mfma_f32_16x16x32_bf16 v[12:15], v[154:157], v[0:3], v[158:161]
	v_lshl_add_u64 v[0:1], v[8:9], 0, v[48:49]
	v_lshl_add_u64 v[120:121], v[0:1], 0, s[26:27]
	v_lshl_add_u64 v[142:143], v[120:121], 0, s[28:29]
	v_add_co_u32_e32 v120, vcc, s37, v120
	ds_read_b128 v[4:7], v94
	s_nop 0
	v_addc_co_u32_e32 v121, vcc, 0, v121, vcc
	ds_read_b128 v[0:3], v95
	ds_read_b128 v[158:161], v96
	global_load_ushort v123, v[120:121], off
	global_load_ushort v122, v[142:143], off offset:32
	s_nop 0
	global_load_ushort v121, v[142:143], off offset:64
	global_load_ushort v120, v[142:143], off offset:96
	global_load_ushort v65, v[142:143], off offset:128
	global_load_ushort v49, v[142:143], off offset:160
	global_load_ushort v47, v[142:143], off offset:192
	global_load_ushort v38, v[142:143], off offset:224
	s_waitcnt lgkmcnt(2)
	v_mfma_f32_16x16x32_bf16 v[8:11], v[154:157], v[4:7], v[162:165]
	v_mul_f32_e32 v132, v24, v24
	v_mul_f32_e32 v136, v25, v25
	v_mul_f32_e32 v142, v26, v26
	s_waitcnt lgkmcnt(1)
	v_mfma_f32_16x16x32_bf16 v[4:7], v[154:157], v[0:3], v[166:169]
	v_fmac_f32_e32 v132, v28, v28
	v_fmac_f32_e32 v136, v29, v29
	v_fmac_f32_e32 v142, v30, v30
	s_waitcnt lgkmcnt(0)
	v_mfma_f32_16x16x32_bf16 v[0:3], v[154:157], v[158:161], v[150:153]
	v_fmac_f32_e32 v132, v20, v20
	v_fmac_f32_e32 v136, v21, v21
	v_fmac_f32_e32 v142, v22, v22
	v_mul_f32_e32 v150, v27, v27
	v_fmac_f32_e32 v150, v31, v31
	v_fmac_f32_e32 v150, v23, v23
	v_fmac_f32_e32 v132, v16, v16
	v_fmac_f32_e32 v136, v17, v17
	v_fmac_f32_e32 v142, v18, v18
	v_fmac_f32_e32 v150, v19, v19
	v_fmac_f32_e32 v132, v12, v12
	v_fmac_f32_e32 v136, v13, v13
	v_fmac_f32_e32 v142, v14, v14
	v_fmac_f32_e32 v150, v15, v15
	v_fmac_f32_e32 v132, v8, v8
	v_fmac_f32_e32 v136, v9, v9
	v_fmac_f32_e32 v142, v10, v10
	v_fmac_f32_e32 v150, v11, v11
	v_fmac_f32_e32 v132, v4, v4
	v_fmac_f32_e32 v136, v5, v5
	v_fmac_f32_e32 v142, v6, v6
	v_fmac_f32_e32 v150, v7, v7
	v_fmac_f32_e32 v132, v0, v0
	v_fmac_f32_e32 v136, v1, v1
	v_fmac_f32_e32 v142, v2, v2
	v_fmac_f32_e32 v150, v3, v3
	ds_bpermute_b32 v135, v70, v132
	ds_bpermute_b32 v140, v70, v136
	ds_bpermute_b32 v143, v70, v142
	ds_bpermute_b32 v151, v70, v150
	s_waitcnt lgkmcnt(3)
	v_add_f32_e32 v132, v132, v135
	s_waitcnt lgkmcnt(2)
	v_add_f32_e32 v136, v136, v140
	s_waitcnt lgkmcnt(1)
	v_add_f32_e32 v142, v142, v143
	s_waitcnt lgkmcnt(0)
	v_add_f32_e32 v150, v150, v151
	ds_bpermute_b32 v135, v71, v132
	ds_bpermute_b32 v140, v71, v136
	ds_bpermute_b32 v143, v71, v142
	ds_bpermute_b32 v151, v71, v150
	s_waitcnt lgkmcnt(3)
	v_add_f32_e32 v132, v132, v135
	s_waitcnt lgkmcnt(2)
	v_add_f32_e32 v136, v136, v140
	s_waitcnt lgkmcnt(1)
	v_add_f32_e32 v142, v142, v143
	s_waitcnt lgkmcnt(0)
	v_add_f32_e32 v150, v150, v151
	ds_bpermute_b32 v135, v72, v132
	ds_bpermute_b32 v140, v72, v136
	ds_bpermute_b32 v143, v72, v142
	ds_bpermute_b32 v151, v72, v150
	s_waitcnt lgkmcnt(3)
	v_add_f32_e32 v132, v132, v135
	s_waitcnt lgkmcnt(2)
	v_add_f32_e32 v136, v136, v140
	s_waitcnt lgkmcnt(1)
	v_add_f32_e32 v142, v142, v143
	s_waitcnt lgkmcnt(0)
	v_add_f32_e32 v150, v150, v151
	ds_bpermute_b32 v135, v73, v132
	ds_bpermute_b32 v140, v73, v136
	ds_bpermute_b32 v143, v73, v142
	ds_bpermute_b32 v151, v73, v150
	s_and_saveexec_b64 s[40:41], s[0:1]
	s_cbranch_execz .LBB0_1927
	s_waitcnt lgkmcnt(3)
	v_add_f32_e32 v132, v132, v135
	v_add_u32_e32 v135, s25, v97
	s_waitcnt lgkmcnt(1)
	v_add_f32_e32 v142, v142, v143
	v_add_f32_e32 v136, v136, v140
	ds_write_b32 v135, v132
	ds_write_b32 v114, v136
	v_add_u32_e32 v132, s25, v98
	s_waitcnt lgkmcnt(2)
	v_add_f32_e32 v150, v150, v151
	ds_write_b32 v132, v142
	ds_write_b32 v115, v150
	s_branch .LBB0_1927
